# first seam (prep->layer0): cg grid.sync replaced by cookie broadcast from WG0 after counter zeroing + XCD-hierarchical barrier (round=ph+1); WG0 clears cookie at kernel end
# speedup vs baseline: 1.1639x; 1.0153x over previous
; __global__ void __launch_bounds__(NTHR) mega_fwd(Params p) {
;     extern __shared__ __attribute__((aligned(16))) char lds[];
;     cg::grid_group grid = cg::this_grid();
;     const int nb = gridDim.x, bid = blockIdx.x;
;     if (bid == 0 && threadIdx.x < 256) __hip_atomic_store(WS_PTR(unsigned, OFF_HL) + threadIdx.x, 0u, __ATOMIC_RELAXED, __HIP_MEMORY_SCOPE_AGENT);
;     prep_phase(p, lds);
;     unsigned* bar = WS_PTR(unsigned, OFF_HL);
;     for (int ph = 0; ph < 4; ++ph) {
;         if (ph == 0) grid.sync(); else fast_grid_barrier(bar, (unsigned)ph * (unsigned)nb);
.LBB0_2:
	s_or_b64 exec, exec, s[2:3]
	s_cmp_lg_u32 s50, 0
	s_cbranch_scc1 .Lck_skip
	s_waitcnt vmcnt(0)
	s_barrier
	v_cmp_eq_u32_e32 vcc, 0, v212
	s_and_saveexec_b64 s[4:5], vcc
	s_cbranch_execz .Lck_pub_done
	s_load_dwordx2 s[6:7], s[0:1], 0xb8
	v_mov_b32_e32 v2, 0x3c7e19a5
	v_mov_b32_e32 v3, 1200
	s_waitcnt lgkmcnt(0)
	s_add_u32 s6, s6, 0x17000000
	s_addc_u32 s7, s7, 0
	global_store_dword v3, v2, s[6:7] sc1
.Lck_pub_done:
	s_or_b64 exec, exec, s[4:5]
.Lck_skip:
	s_load_dwordx16 s[52:67], s[0:1], 0x0
	s_load_dwordx16 s[4:19], s[0:1], 0x40
	v_mov_b32_e32 v2, v212
	s_cmp_gt_i32 s50, 31
	v_and_b32_e32 v21, 63, v212
	s_waitcnt lgkmcnt(0)
	v_writelane_b32 v244, s4, 20
	s_nop 1
	v_writelane_b32 v244, s5, 21
	v_writelane_b32 v244, s6, 22
	v_writelane_b32 v244, s7, 23
	v_writelane_b32 v244, s8, 24
	v_writelane_b32 v244, s9, 25
	v_writelane_b32 v244, s10, 26
	v_writelane_b32 v244, s11, 27
	v_writelane_b32 v244, s12, 28
	v_writelane_b32 v244, s13, 29
	v_writelane_b32 v244, s14, 30
	v_writelane_b32 v244, s15, 31
	v_writelane_b32 v244, s16, 32
	v_writelane_b32 v244, s17, 33
	v_writelane_b32 v244, s18, 34
	v_writelane_b32 v244, s19, 35
	s_cbranch_scc1 .LBB0_27
	v_readlane_b32 s8, v244, 0
	v_readlane_b32 s22, v244, 14
	v_readlane_b32 s23, v244, 15
	s_add_u32 s2, s22, 0x18d80000
	v_lshrrev_b32_e32 v5, 2, v212
	v_readlane_b32 s12, v244, 4
	s_addc_u32 s3, s23, 0
	v_and_b32_e32 v5, 0xfc, v5
	v_readlane_b32 s13, v244, 5
	s_add_u32 s12, s22, 0x18d84000
	v_readlane_b32 s6, v244, 18
	v_add_u32_e32 v5, 0, v5
	s_addc_u32 s13, s23, 0
	v_readlane_b32 s7, v244, 19
	s_mov_b32 s8, s6
	s_lshl_b32 s26, s6, 10
	v_add_u32_e32 v25, 0x1200, v5
	v_lshlrev_b32_e32 v5, 4, v212
	s_mul_i32 s6, s50, 0x18000
	v_and_b32_e32 v5, 0xf00, v5
	s_mul_hi_i32 s7, s50, 0x18000
	s_add_u32 s6, s22, s6
	v_and_b32_e32 v3, 15, v212
	v_readlane_b32 s20, v244, 12
	v_add_u32_e32 v5, 0, v5
	v_lshlrev_b32_e32 v6, 1, v212
	v_mov_b32_e32 v7, 0
	s_addc_u32 s7, s23, s7
	v_lshl_add_u32 v1, v212, 2, 0
	v_and_b32_e32 v4, 0x7f, v212
	v_bfe_u32 v20, v212, 4, 3
	v_readlane_b32 s14, v244, 6
	v_readlane_b32 s15, v244, 7
	v_readlane_b32 s16, v244, 8
	v_readlane_b32 s17, v244, 9
	v_readlane_b32 s18, v244, 10
	v_readlane_b32 s19, v244, 11
	s_mov_b32 s20, s50
	v_add_u32_e32 v27, 0x3400, v5
	v_lshl_add_u32 v5, v3, 2, 0
	v_lshl_add_u64 v[8:9], s[6:7], 0, v[6:7]
	s_mov_b64 s[6:7], 0x18a80000
	v_cmp_gt_u32_e64 s[0:1], 64, v212
	v_lshlrev_b32_e32 v22, 6, v20
	v_cmp_gt_u32_e64 s[4:5], 64, v4
	v_add_u32_e32 v23, 0x1400, v1
	v_add_u32_e32 v24, 0xfffffe00, v212
	v_lshl_or_b32 v4, s20, 10, v212
	v_lshrrev_b32_e32 v26, 8, v212
	v_add_u32_e32 v28, 0x1400, v5
	v_lshl_add_u64 v[8:9], v[8:9], 0, s[6:7]
	s_mul_hi_i32 s15, s8, 0x18000
	s_mul_i32 s14, s8, 0x18000
	v_lshrrev_b32_e32 v29, 7, v212
	s_brev_b32 s27, 18
	s_mov_b32 s28, 0xfe5163ab
	s_mov_b32 s29, 0x3c439041
	s_mov_b32 s30, 0xdb629599
	s_mov_b32 s31, 0xf534ddc0
	s_mov_b32 s33, 0xfc2757d1
	s_mov_b32 s34, 0x4e441529
	s_mov_b32 s35, 0xa2f9836e
	s_mov_b32 s36, 0x3fc90fda
	s_mov_b32 s37, 0x3f22f983
	s_mov_b32 s38, 0xbfc90fda
	s_mov_b32 s39, 0xc2ce8ed0
	s_mov_b32 s40, 0x42b17218
	v_mov_b32_e32 v30, 0x3c0881c4
	v_mov_b32_e32 v31, 0xbab64f3b
	v_mov_b32_e32 v32, 1.0
	s_movk_i32 s41, 0x1f8
	v_mov_b32_e32 v33, 0x3ab69700
	s_mov_b32 s42, 0x43000000
	s_mov_b32 s43, 0x42b17217
	s_mov_b32 s44, 0xc1880000
	s_mov_b64 s[16:17], 0x800
	s_movk_i32 s45, 0x5ff
	s_movk_i32 s46, 0x1c0
	s_movk_i32 s47, 0x2000
	s_mov_b32 s48, 0x8000
	s_mov_b64 s[18:19], 0x400
	s_movk_i32 s49, 0x3dff
	v_not_b32_e32 v34, 63
	v_not_b32_e32 v35, 31
	v_mov_b32_e32 v36, 0x7f800000
	v_mov_b32_e32 v37, 0x7fc00000
	v_mov_b32_e32 v38, 0x7f000000
	v_mov_b32_e32 v11, 2.0
	v_readlane_b32 s9, v244, 1
	v_readlane_b32 s10, v244, 2
	v_readlane_b32 s11, v244, 3
	v_readlane_b32 s21, v244, 13
	s_branch .LBB0_5

; template <int N> DI void wait_vm() { asm volatile("s_waitcnt vmcnt(%0)" ::"n"(N) : "memory"); }
; DI void signal_done(unsigned* c) {
;     wait_vm<0>();
;     __syncthreads();
;     if (threadIdx.x == 0) { __builtin_amdgcn_fence(__ATOMIC_RELEASE, "agent"); __hip_atomic_fetch_add(c, 1u, __ATOMIC_RELAXED, __HIP_MEMORY_SCOPE_AGENT); }
; }
; __global__ void __launch_bounds__(NTHR) mega_fwd(Params p) {
;     ...
;     if (bid == 0 && threadIdx.x < 256) __hip_atomic_store(WS_PTR(unsigned, OFF_HL) + threadIdx.x, 0u, __ATOMIC_RELAXED, __HIP_MEMORY_SCOPE_AGENT);
.LBB0_53:
	s_or_b64 exec, exec, s[0:1]
	v_cmp_eq_u32_e32 vcc, 0, v212
	s_and_saveexec_b64 s[0:1], vcc
	s_cbranch_execz .Lck_posted
	v_readlane_b32 s2, v244, 14
	v_readlane_b32 s3, v244, 15
	s_nop 3
	s_add_u32 s2, s2, 0x17000000
	s_addc_u32 s3, s3, 0
	s_mov_b32 s4, 0x3c7e19a5
	v_mov_b32_e32 v3, 1200
.Lck_wait:
	global_load_dword v4, v3, s[2:3] sc1
	s_waitcnt vmcnt(0)
	v_cmp_ne_u32_e32 vcc, s4, v4
	s_cbranch_vccz .Lck_ok
	s_sleep 2
	s_branch .Lck_wait
.Lck_ok:
	s_getreg_b32 s4, hwreg(HW_REG_XCC_ID, 0, 4)
	s_lshl_b32 s4, s4, 2
	v_mov_b32_e32 v5, s4
	v_add_u32_e32 v5, 0x280, v5
	v_mov_b32_e32 v6, 1
	s_nop 1
	global_atomic_add v5, v6, s[2:3]

; template <int N> DI void wait_vm() { asm volatile("s_waitcnt vmcnt(%0)" ::"n"(N) : "memory"); }
; DI void fast_grid_barrier(unsigned* ctr, unsigned target) {
;     wait_vm<0>();
;     __syncthreads();
;     if (threadIdx.x == 0) {
;         __builtin_amdgcn_fence(__ATOMIC_RELEASE, "agent");
;         __hip_atomic_fetch_add(ctr, 1u, __ATOMIC_RELAXED, __HIP_MEMORY_SCOPE_AGENT);
;         while (__hip_atomic_load(ctr, __ATOMIC_RELAXED, __HIP_MEMORY_SCOPE_AGENT) < target) __builtin_amdgcn_s_sleep(6);
;         __builtin_amdgcn_fence(__ATOMIC_ACQUIRE, "agent");
;     }
;     __syncthreads();
; }
; __global__ void __launch_bounds__(NTHR) mega_fwd(Params p) {
;     ...
;     for (int ph = 0; ph < 4; ++ph) {
;         if (ph == 0) grid.sync(); else fast_grid_barrier(bar, (unsigned)ph * (unsigned)nb);
.LBB0_62:
	s_waitcnt vmcnt(0)
	s_barrier
	s_mov_b64 s[0:1], exec
	v_readlane_b32 s2, v243, 32
	v_readlane_b32 s3, v243, 33
	s_and_b64 s[2:3], s[0:1], s[2:3]
	s_mov_b64 exec, s[2:3]
	s_cbranch_execz .LBB0_69
	v_readlane_b32 s10, v244, 42
	v_readlane_b32 s11, v244, 43
	s_getreg_b32 s6, hwreg(HW_REG_XCC_ID, 0, 4)
	s_lshl_b32 s6, s6, 2
	v_mov_b32_e32 v2, s6
	v_mov_b32_e32 v3, 1
	v_readlane_b32 s3, v245, 0
	s_nop 3
	s_cmp_lg_u32 s3, 0
	s_cbranch_scc1 .Lcen_xb_done
	v_readlane_b32 s2, v244, 18

; template <int N> DI void wait_vm() { asm volatile("s_waitcnt vmcnt(%0)" ::"n"(N) : "memory"); }
; DI void fast_grid_barrier(unsigned* ctr, unsigned target) {
;     wait_vm<0>();
;     __syncthreads();
;     if (threadIdx.x == 0) {
;         __builtin_amdgcn_fence(__ATOMIC_RELEASE, "agent");
;         __hip_atomic_fetch_add(ctr, 1u, __ATOMIC_RELAXED, __HIP_MEMORY_SCOPE_AGENT);
;         while (__hip_atomic_load(ctr, __ATOMIC_RELAXED, __HIP_MEMORY_SCOPE_AGENT) < target) __builtin_amdgcn_s_sleep(6);
;         __builtin_amdgcn_fence(__ATOMIC_ACQUIRE, "agent");
;     }
;     __syncthreads();
; }
.Lcen_xb_done:
	s_add_u32 s2, s12, 1
	v_add_u32_e32 v23, 0x2c0, v2
	v_add_u32_e32 v24, 0x300, v2
	v_mov_b32_e32 v25, 0x340
	v_mov_b32_e32 v26, 0x344
	global_atomic_add v0, v23, v3, s[10:11] sc0
	s_waitcnt vmcnt(0)
	v_readfirstlane_b32 s6, v0
	s_nop 3
	s_add_u32 s6, s6, 1
	s_mul_i32 s7, s2, s3
	s_cmp_eq_u32 s6, s7
	s_cbranch_scc0 .Lxb_follow
	buffer_wbl2 sc1
	s_waitcnt vmcnt(0)
	global_atomic_add v0, v25, v3, s[10:11] sc0
	s_waitcnt vmcnt(0)
	v_readfirstlane_b32 s6, v0
	v_readlane_b32 s7, v245, 1
	s_nop 3
	s_add_u32 s6, s6, 1
	s_mul_i32 s7, s2, s7
	s_cmp_eq_u32 s6, s7
	s_cbranch_scc0 .Lxb_wait_top
	global_atomic_add v26, v3, s[10:11]
	s_branch .Lxb_top_done
.Lxb_wait_top:
	s_sleep 1
	global_load_dword v0, v26, s[10:11] sc1
	s_waitcnt vmcnt(0)
	v_cmp_gt_u32_e32 vcc, s2, v0
	s_cbranch_vccnz .Lxb_wait_top

; template <int N> DI void wait_vm() { asm volatile("s_waitcnt vmcnt(%0)" ::"n"(N) : "memory"); }
; DI void fast_grid_barrier(unsigned* ctr, unsigned target) {
;     wait_vm<0>();
;     __syncthreads();
;     if (threadIdx.x == 0) {
;         __builtin_amdgcn_fence(__ATOMIC_RELEASE, "agent");
;         __hip_atomic_fetch_add(ctr, 1u, __ATOMIC_RELAXED, __HIP_MEMORY_SCOPE_AGENT);
;         while (__hip_atomic_load(ctr, __ATOMIC_RELAXED, __HIP_MEMORY_SCOPE_AGENT) < target) __builtin_amdgcn_s_sleep(6);
;         __builtin_amdgcn_fence(__ATOMIC_ACQUIRE, "agent");
;     }
;     __syncthreads();
; }
.Lxb_follow:
	s_sleep 1
	global_load_dword v0, v24, s[10:11] sc1
	s_waitcnt vmcnt(0)
	v_cmp_gt_u32_e32 vcc, s2, v0
	s_cbranch_vccnz .Lxb_follow
	buffer_inv sc1
	s_waitcnt vmcnt(0)

; __global__ void __launch_bounds__(NTHR) mega_fwd(Params p) {
;     extern __shared__ __attribute__((aligned(16))) char lds[];
;     cg::grid_group grid = cg::this_grid();
;     const int nb = gridDim.x, bid = blockIdx.x;
;     if (bid == 0 && threadIdx.x < 256) __hip_atomic_store(WS_PTR(unsigned, OFF_HL) + threadIdx.x, 0u, __ATOMIC_RELAXED, __HIP_MEMORY_SCOPE_AGENT);
;     prep_phase(p, lds);
.LBB0_1092:
	s_mov_b64 exec, -1
	v_readlane_b32 s0, v244, 36
	s_nop 3
	s_cmp_lg_u32 s0, 0
	s_cbranch_scc1 .Lck_end
	v_cmp_eq_u32_e32 vcc, 0, v212
	s_and_saveexec_b64 s[0:1], vcc
	s_cbranch_execz .Lck_end
	v_readlane_b32 s2, v244, 42
	v_readlane_b32 s3, v244, 43
	v_mov_b32_e32 v2, 0
	v_mov_b32_e32 v3, 1200
	s_nop 4
	global_store_dword v3, v2, s[2:3] sc1
